# G3 q/k epilogue: QK-norm gain vector loads hoisted (4 preloaded f32x4), 32 vmcnt(0) store-drain waits removed
# speedup vs baseline: 1.0052x; 1.0052x over previous
.LBB0_750:
	s_and_b64 s[8:9], s[44:45], exec
	s_cselect_b32 s8, s48, s50
	s_cselect_b32 s9, s49, s51
	s_add_u32 s8, s8, s60
	v_cndmask_b32_e64 v130, 0, 1, s[76:77]
	s_addc_u32 s9, s9, s61
	v_lshlrev_b32_e32 v0, 2, v144
	v_cmp_ne_u32_e64 s[40:41], 1, v130
	v_mov_b64_e32 v[132:133], v[128:129]
	v_lshl_add_u64 v[152:153], s[8:9], 0, v[0:1]
	global_load_dwordx4 v[224:227], v[152:153], off
	global_load_dwordx4 v[228:231], v[152:153], off offset:16
	global_load_dwordx4 v[232:235], v[152:153], off offset:128
	global_load_dwordx4 v[236:239], v[152:153], off offset:144
	s_waitcnt vmcnt(0)
	s_andn2_b64 vcc, exec, s[76:77]
	v_mov_b32_e32 v159, v158
	v_mov_b64_e32 v[130:131], v[126:127]
	s_cbranch_vccnz .LBB0_752
	v_mov_b64_e32 v[130:131], v[224:225]
	v_mov_b64_e32 v[132:133], v[226:227]
	v_mov_b32_e32 v134, v158
	v_mov_b32_e32 v135, v158
	v_pk_mul_f32 v[132:133], v[128:129], v[132:133]
	v_pk_mul_f32 v[130:131], v[126:127], v[130:131]
	v_pk_mul_f32 v[132:133], v[134:135], v[132:133]
	v_pk_mul_f32 v[130:131], v[158:159], v[130:131]

.LBB0_754:
	s_nop 1
	v_cvt_pk_bf16_f32 v130, v130, v131
	v_cvt_pk_bf16_f32 v131, v132, v133
	v_mov_b64_e32 v[134:135], v[124:125]
	s_and_b64 vcc, exec, s[40:41]
	v_mov_b64_e32 v[132:133], v[122:123]
	s_cbranch_vccnz .LBB0_756
	v_mov_b64_e32 v[132:133], v[228:229]
	v_mov_b64_e32 v[134:135], v[230:231]
	v_mov_b32_e32 v156, v158
	v_mov_b32_e32 v157, v158
	v_pk_mul_f32 v[134:135], v[124:125], v[134:135]
	v_pk_mul_f32 v[132:133], v[122:123], v[132:133]
	v_pk_mul_f32 v[134:135], v[156:157], v[134:135]
	v_pk_mul_f32 v[132:133], v[158:159], v[132:133]

.LBB0_758:
	s_lshl_b32 s5, s5, 6
	s_and_b64 s[0:1], s[44:45], exec
	s_movk_i32 s0, 0x1080
	s_cselect_b32 s8, 0x100, s0
	s_and_b64 s[0:1], exec, s[74:75]
	s_cselect_b32 s0, s8, 32
	s_lshl_b32 s1, s5, 1
	s_add_u32 s8, s58, s1
	s_addc_u32 s9, s59, 0
	v_lshlrev_b32_e32 v0, 1, v144
	v_ashrrev_i32_e32 v151, 5, v150
	v_lshl_add_u64 v[156:157], s[8:9], 0, v[0:1]
	v_and_b32_e32 v0, 31, v150
	v_mad_i64_i32 v[162:163], s[8:9], s0, v151, 0
	v_or_b32_e32 v162, v162, v0
	v_lshlrev_b64 v[162:163], 10, v[162:163]
	v_lshl_add_u64 v[162:163], v[156:157], 0, v[162:163]
	v_cvt_pk_bf16_f32 v132, v132, v133
	v_cvt_pk_bf16_f32 v133, v134, v135
	global_store_dwordx4 v[162:163], v[130:133], off
	s_and_b64 vcc, exec, s[40:41]
	s_nop 0
	v_mov_b64_e32 v[132:133], v[112:113]
	v_mov_b64_e32 v[130:131], v[110:111]
	s_cbranch_vccnz .LBB0_760
	v_mov_b64_e32 v[130:131], v[232:233]
	v_mov_b64_e32 v[132:133], v[234:235]
	v_mov_b32_e32 v134, v158
	v_mov_b32_e32 v135, v158
	v_pk_mul_f32 v[132:133], v[112:113], v[132:133]
	v_pk_mul_f32 v[130:131], v[110:111], v[130:131]
	v_pk_mul_f32 v[132:133], v[134:135], v[132:133]
	v_pk_mul_f32 v[130:131], v[158:159], v[130:131]

.LBB0_762:
	s_nop 1
	v_cvt_pk_bf16_f32 v130, v130, v131
	v_cvt_pk_bf16_f32 v131, v132, v133
	v_mov_b64_e32 v[134:135], v[104:105]
	s_and_b64 vcc, exec, s[40:41]
	v_mov_b64_e32 v[132:133], v[102:103]
	s_cbranch_vccnz .LBB0_764
	v_mov_b64_e32 v[132:133], v[236:237]
	v_mov_b64_e32 v[134:135], v[238:239]
	v_mov_b32_e32 v166, v158
	v_mov_b32_e32 v167, v158
	v_pk_mul_f32 v[134:135], v[104:105], v[134:135]
	v_pk_mul_f32 v[132:133], v[102:103], v[132:133]
	v_pk_mul_f32 v[134:135], v[166:167], v[134:135]
	v_pk_mul_f32 v[132:133], v[158:159], v[132:133]

.LBB0_768:
	v_mov_b64_e32 v[132:133], v[120:121]
	s_and_b64 vcc, exec, s[40:41]
	v_mov_b32_e32 v159, v158
	v_mov_b64_e32 v[130:131], v[118:119]
	s_cbranch_vccnz .LBB0_770
	v_mov_b64_e32 v[130:131], v[224:225]
	v_mov_b64_e32 v[132:133], v[226:227]
	v_mov_b32_e32 v134, v158
	v_mov_b32_e32 v135, v158
	v_pk_mul_f32 v[132:133], v[120:121], v[132:133]
	v_pk_mul_f32 v[130:131], v[118:119], v[130:131]
	v_pk_mul_f32 v[132:133], v[134:135], v[132:133]
	v_pk_mul_f32 v[130:131], v[158:159], v[130:131]

.LBB0_772:
	s_nop 1
	v_cvt_pk_bf16_f32 v130, v130, v131
	v_cvt_pk_bf16_f32 v131, v132, v133
	v_mov_b64_e32 v[134:135], v[116:117]
	s_and_b64 vcc, exec, s[40:41]
	v_mov_b64_e32 v[132:133], v[114:115]
	s_cbranch_vccnz .LBB0_774
	v_mov_b64_e32 v[132:133], v[228:229]
	v_mov_b64_e32 v[134:135], v[230:231]
	v_mov_b32_e32 v166, v158
	v_mov_b32_e32 v167, v158
	v_pk_mul_f32 v[134:135], v[116:117], v[134:135]
	v_pk_mul_f32 v[132:133], v[114:115], v[132:133]
	v_pk_mul_f32 v[134:135], v[166:167], v[134:135]
	v_pk_mul_f32 v[132:133], v[158:159], v[132:133]

.LBB0_776:
	v_ashrrev_i32_e32 v151, 5, v162
	v_mad_i64_i32 v[162:163], s[8:9], s0, v151, 0
	v_bitop3_b32 v162, v162, v0, 16 bitop3:0xf6
	v_lshlrev_b64 v[162:163], 10, v[162:163]
	v_lshl_add_u64 v[162:163], v[156:157], 0, v[162:163]
	v_cvt_pk_bf16_f32 v132, v132, v133
	v_cvt_pk_bf16_f32 v133, v134, v135
	global_store_dwordx4 v[162:163], v[130:133], off
	s_and_b64 vcc, exec, s[40:41]
	s_nop 0
	v_mov_b64_e32 v[132:133], v[96:97]
	v_mov_b64_e32 v[130:131], v[94:95]
	s_cbranch_vccnz .LBB0_778
	v_mov_b64_e32 v[130:131], v[232:233]
	v_mov_b64_e32 v[132:133], v[234:235]
	v_mov_b32_e32 v134, v158
	v_mov_b32_e32 v135, v158
	v_pk_mul_f32 v[132:133], v[96:97], v[132:133]
	v_pk_mul_f32 v[130:131], v[94:95], v[130:131]
	v_pk_mul_f32 v[132:133], v[134:135], v[132:133]
	v_pk_mul_f32 v[130:131], v[158:159], v[130:131]

.LBB0_780:
	s_nop 1
	v_cvt_pk_bf16_f32 v130, v130, v131
	v_cvt_pk_bf16_f32 v131, v132, v133
	v_mov_b64_e32 v[134:135], v[88:89]
	s_and_b64 vcc, exec, s[40:41]
	v_mov_b64_e32 v[132:133], v[86:87]
	s_cbranch_vccnz .LBB0_782
	v_mov_b64_e32 v[132:133], v[236:237]
	v_mov_b64_e32 v[134:135], v[238:239]
	v_mov_b32_e32 v166, v158
	v_mov_b32_e32 v167, v158
	v_pk_mul_f32 v[134:135], v[88:89], v[134:135]
	v_pk_mul_f32 v[132:133], v[86:87], v[132:133]
	v_pk_mul_f32 v[134:135], v[166:167], v[134:135]
	v_pk_mul_f32 v[132:133], v[158:159], v[132:133]

.LBB0_786:
	v_mov_b64_e32 v[132:133], v[108:109]
	s_and_b64 vcc, exec, s[40:41]
	v_mov_b32_e32 v159, v158
	v_mov_b64_e32 v[130:131], v[106:107]
	s_cbranch_vccnz .LBB0_788
	v_mov_b64_e32 v[130:131], v[224:225]
	v_mov_b64_e32 v[132:133], v[226:227]
	v_mov_b32_e32 v134, v158
	v_mov_b32_e32 v135, v158
	v_pk_mul_f32 v[132:133], v[108:109], v[132:133]
	v_pk_mul_f32 v[130:131], v[106:107], v[130:131]
	v_pk_mul_f32 v[132:133], v[134:135], v[132:133]
	v_pk_mul_f32 v[130:131], v[158:159], v[130:131]

.LBB0_790:
	s_nop 1
	v_cvt_pk_bf16_f32 v130, v130, v131
	v_cvt_pk_bf16_f32 v131, v132, v133
	v_mov_b64_e32 v[134:135], v[100:101]
	s_and_b64 vcc, exec, s[40:41]
	v_mov_b64_e32 v[132:133], v[98:99]
	s_cbranch_vccnz .LBB0_792
	v_mov_b64_e32 v[132:133], v[228:229]
	v_mov_b64_e32 v[134:135], v[230:231]
	v_mov_b32_e32 v166, v158
	v_mov_b32_e32 v167, v158
	v_pk_mul_f32 v[134:135], v[100:101], v[134:135]
	v_pk_mul_f32 v[132:133], v[98:99], v[132:133]
	v_pk_mul_f32 v[134:135], v[166:167], v[134:135]
	v_pk_mul_f32 v[132:133], v[158:159], v[132:133]

.LBB0_794:
	v_ashrrev_i32_e32 v151, 5, v162
	v_mad_i64_i32 v[162:163], s[8:9], s0, v151, 0
	v_or_b32_e32 v162, v162, v0
	v_lshlrev_b64 v[162:163], 10, v[162:163]
	v_lshl_add_u64 v[162:163], v[156:157], 0, v[162:163]
	v_cvt_pk_bf16_f32 v132, v132, v133
	v_cvt_pk_bf16_f32 v133, v134, v135
	global_store_dwordx4 v[162:163], v[130:133], off
	s_and_b64 vcc, exec, s[40:41]
	s_nop 0
	v_mov_b64_e32 v[132:133], v[80:81]
	v_mov_b64_e32 v[130:131], v[78:79]
	s_cbranch_vccnz .LBB0_796
	v_mov_b64_e32 v[130:131], v[232:233]
	v_mov_b64_e32 v[132:133], v[234:235]
	v_mov_b32_e32 v134, v158
	v_mov_b32_e32 v135, v158
	v_pk_mul_f32 v[132:133], v[80:81], v[132:133]
	v_pk_mul_f32 v[130:131], v[78:79], v[130:131]
	v_pk_mul_f32 v[132:133], v[134:135], v[132:133]
	v_pk_mul_f32 v[130:131], v[158:159], v[130:131]

.LBB0_798:
	s_nop 1
	v_cvt_pk_bf16_f32 v130, v130, v131
	v_cvt_pk_bf16_f32 v131, v132, v133
	v_mov_b64_e32 v[134:135], v[76:77]
	s_and_b64 vcc, exec, s[40:41]
	v_mov_b64_e32 v[132:133], v[74:75]
	s_cbranch_vccnz .LBB0_800
	v_mov_b64_e32 v[132:133], v[236:237]
	v_mov_b64_e32 v[134:135], v[238:239]
	v_mov_b32_e32 v166, v158
	v_mov_b32_e32 v167, v158
	v_pk_mul_f32 v[134:135], v[76:77], v[134:135]
	v_pk_mul_f32 v[132:133], v[74:75], v[132:133]
	v_pk_mul_f32 v[134:135], v[166:167], v[134:135]
	v_pk_mul_f32 v[132:133], v[158:159], v[132:133]

.LBB0_804:
	v_mov_b64_e32 v[132:133], v[92:93]
	s_and_b64 vcc, exec, s[40:41]
	v_mov_b32_e32 v159, v158
	v_mov_b64_e32 v[130:131], v[90:91]
	s_cbranch_vccnz .LBB0_806
	v_mov_b64_e32 v[130:131], v[224:225]
	v_mov_b64_e32 v[132:133], v[226:227]
	v_mov_b32_e32 v134, v158
	v_mov_b32_e32 v135, v158
	v_pk_mul_f32 v[132:133], v[92:93], v[132:133]
	v_pk_mul_f32 v[130:131], v[90:91], v[130:131]
	v_pk_mul_f32 v[132:133], v[134:135], v[132:133]
	v_pk_mul_f32 v[130:131], v[158:159], v[130:131]

.LBB0_808:
	s_nop 1
	v_cvt_pk_bf16_f32 v130, v130, v131
	v_cvt_pk_bf16_f32 v131, v132, v133
	v_mov_b64_e32 v[134:135], v[84:85]
	s_and_b64 vcc, exec, s[40:41]
	v_mov_b64_e32 v[132:133], v[82:83]
	s_cbranch_vccnz .LBB0_810
	v_mov_b64_e32 v[132:133], v[228:229]
	v_mov_b64_e32 v[134:135], v[230:231]
	v_mov_b32_e32 v166, v158
	v_mov_b32_e32 v167, v158
	v_pk_mul_f32 v[134:135], v[84:85], v[134:135]
	v_pk_mul_f32 v[132:133], v[82:83], v[132:133]
	v_pk_mul_f32 v[134:135], v[166:167], v[134:135]
	v_pk_mul_f32 v[132:133], v[158:159], v[132:133]

.LBB0_812:
	v_ashrrev_i32_e32 v162, 5, v162
	v_xor_b32_e32 v151, 16, v0
	v_mad_i64_i32 v[162:163], s[8:9], s0, v162, 0
	v_or_b32_e32 v162, v162, v151
	v_lshlrev_b64 v[162:163], 10, v[162:163]
	v_lshl_add_u64 v[162:163], v[156:157], 0, v[162:163]
	v_cvt_pk_bf16_f32 v132, v132, v133
	v_cvt_pk_bf16_f32 v133, v134, v135
	global_store_dwordx4 v[162:163], v[130:133], off
	s_and_b64 vcc, exec, s[40:41]
	s_nop 0
	v_mov_b64_e32 v[132:133], v[72:73]
	v_mov_b64_e32 v[130:131], v[70:71]
	s_cbranch_vccnz .LBB0_814
	v_mov_b64_e32 v[130:131], v[232:233]
	v_mov_b64_e32 v[132:133], v[234:235]
	v_mov_b32_e32 v134, v158
	v_mov_b32_e32 v135, v158
	v_pk_mul_f32 v[132:133], v[72:73], v[132:133]
	v_pk_mul_f32 v[130:131], v[70:71], v[130:131]
	v_pk_mul_f32 v[132:133], v[134:135], v[132:133]
	v_pk_mul_f32 v[130:131], v[158:159], v[130:131]

.LBB0_816:
	s_nop 1
	v_cvt_pk_bf16_f32 v130, v130, v131
	v_cvt_pk_bf16_f32 v131, v132, v133
	v_mov_b64_e32 v[134:135], v[68:69]
	s_and_b64 vcc, exec, s[40:41]
	v_mov_b64_e32 v[132:133], v[66:67]
	s_cbranch_vccnz .LBB0_818
	v_mov_b64_e32 v[132:133], v[236:237]
	v_mov_b64_e32 v[134:135], v[238:239]
	v_mov_b32_e32 v166, v158
	v_mov_b32_e32 v167, v158
	v_pk_mul_f32 v[134:135], v[68:69], v[134:135]
	v_pk_mul_f32 v[132:133], v[66:67], v[132:133]
	v_pk_mul_f32 v[134:135], v[166:167], v[134:135]
	v_pk_mul_f32 v[132:133], v[158:159], v[132:133]

.LBB0_822:
	v_mov_b64_e32 v[132:133], v[64:65]
	s_and_b64 vcc, exec, s[40:41]
	v_mov_b32_e32 v159, v158
	v_mov_b64_e32 v[130:131], v[62:63]
	s_cbranch_vccnz .LBB0_824
	v_mov_b64_e32 v[130:131], v[224:225]
	v_mov_b64_e32 v[132:133], v[226:227]
	v_mov_b32_e32 v134, v158
	v_mov_b32_e32 v135, v158
	v_pk_mul_f32 v[132:133], v[64:65], v[132:133]
	v_pk_mul_f32 v[130:131], v[62:63], v[130:131]
	v_pk_mul_f32 v[132:133], v[134:135], v[132:133]
	v_pk_mul_f32 v[130:131], v[158:159], v[130:131]

.LBB0_826:
	s_nop 1
	v_cvt_pk_bf16_f32 v130, v130, v131
	v_cvt_pk_bf16_f32 v131, v132, v133
	v_mov_b64_e32 v[134:135], v[60:61]
	s_and_b64 vcc, exec, s[40:41]
	v_mov_b64_e32 v[132:133], v[58:59]
	s_cbranch_vccnz .LBB0_828
	v_mov_b64_e32 v[132:133], v[228:229]
	v_mov_b64_e32 v[134:135], v[230:231]
	v_mov_b32_e32 v166, v158
	v_mov_b32_e32 v167, v158
	v_pk_mul_f32 v[134:135], v[60:61], v[134:135]
	v_pk_mul_f32 v[132:133], v[58:59], v[132:133]
	v_pk_mul_f32 v[134:135], v[166:167], v[134:135]
	v_pk_mul_f32 v[132:133], v[158:159], v[132:133]

.LBB0_830:
	v_ashrrev_i32_e32 v162, 5, v162
	v_mad_i64_i32 v[162:163], s[8:9], s0, v162, 0
	v_or_b32_e32 v162, v162, v0
	v_lshlrev_b64 v[162:163], 10, v[162:163]
	v_lshl_add_u64 v[162:163], v[156:157], 0, v[162:163]
	v_cvt_pk_bf16_f32 v132, v132, v133
	v_cvt_pk_bf16_f32 v133, v134, v135
	global_store_dwordx4 v[162:163], v[130:133], off
	s_and_b64 vcc, exec, s[40:41]
	s_nop 0
	v_mov_b64_e32 v[132:133], v[48:49]
	v_mov_b64_e32 v[130:131], v[46:47]
	s_cbranch_vccnz .LBB0_832
	v_mov_b64_e32 v[130:131], v[232:233]
	v_mov_b64_e32 v[132:133], v[234:235]
	v_mov_b32_e32 v134, v158
	v_mov_b32_e32 v135, v158
	v_pk_mul_f32 v[132:133], v[48:49], v[132:133]
	v_pk_mul_f32 v[130:131], v[46:47], v[130:131]
	v_pk_mul_f32 v[132:133], v[134:135], v[132:133]
	v_pk_mul_f32 v[130:131], v[158:159], v[130:131]

.LBB0_834:
	s_nop 1
	v_cvt_pk_bf16_f32 v130, v130, v131
	v_cvt_pk_bf16_f32 v131, v132, v133
	v_mov_b64_e32 v[134:135], v[40:41]
	s_and_b64 vcc, exec, s[40:41]
	v_mov_b64_e32 v[132:133], v[38:39]
	s_cbranch_vccnz .LBB0_836
	v_mov_b64_e32 v[132:133], v[236:237]
	v_mov_b64_e32 v[134:135], v[238:239]
	v_mov_b32_e32 v166, v158
	v_mov_b32_e32 v167, v158
	v_pk_mul_f32 v[134:135], v[40:41], v[134:135]
	v_pk_mul_f32 v[132:133], v[38:39], v[132:133]
	v_pk_mul_f32 v[134:135], v[166:167], v[134:135]
	v_pk_mul_f32 v[132:133], v[158:159], v[132:133]

.LBB0_840:
	v_mov_b64_e32 v[132:133], v[56:57]
	s_and_b64 vcc, exec, s[40:41]
	v_mov_b32_e32 v159, v158
	v_mov_b64_e32 v[130:131], v[54:55]
	s_cbranch_vccnz .LBB0_842
	v_mov_b64_e32 v[130:131], v[224:225]
	v_mov_b64_e32 v[132:133], v[226:227]
	v_mov_b32_e32 v134, v158
	v_mov_b32_e32 v135, v158
	v_pk_mul_f32 v[132:133], v[56:57], v[132:133]
	v_pk_mul_f32 v[130:131], v[54:55], v[130:131]
	v_pk_mul_f32 v[132:133], v[134:135], v[132:133]
	v_pk_mul_f32 v[130:131], v[158:159], v[130:131]

.LBB0_844:
	s_nop 1
	v_cvt_pk_bf16_f32 v130, v130, v131
	v_cvt_pk_bf16_f32 v131, v132, v133
	v_mov_b64_e32 v[134:135], v[52:53]
	s_and_b64 vcc, exec, s[40:41]
	v_mov_b64_e32 v[132:133], v[50:51]
	s_cbranch_vccnz .LBB0_846
	v_mov_b64_e32 v[132:133], v[228:229]
	v_mov_b64_e32 v[134:135], v[230:231]
	v_mov_b32_e32 v166, v158
	v_mov_b32_e32 v167, v158
	v_pk_mul_f32 v[134:135], v[52:53], v[134:135]
	v_pk_mul_f32 v[132:133], v[50:51], v[132:133]
	v_pk_mul_f32 v[134:135], v[166:167], v[134:135]
	v_pk_mul_f32 v[132:133], v[158:159], v[132:133]

.LBB0_848:
	v_ashrrev_i32_e32 v162, 5, v162
	v_mad_i64_i32 v[162:163], s[8:9], s0, v162, 0
	v_or_b32_e32 v162, v162, v151
	v_lshlrev_b64 v[162:163], 10, v[162:163]
	v_lshl_add_u64 v[162:163], v[156:157], 0, v[162:163]
	v_cvt_pk_bf16_f32 v132, v132, v133
	v_cvt_pk_bf16_f32 v133, v134, v135
	global_store_dwordx4 v[162:163], v[130:133], off
	s_and_b64 vcc, exec, s[40:41]
	s_nop 0
	v_mov_b64_e32 v[132:133], v[32:33]
	v_mov_b64_e32 v[130:131], v[30:31]
	s_cbranch_vccnz .LBB0_850
	v_mov_b64_e32 v[130:131], v[232:233]
	v_mov_b64_e32 v[132:133], v[234:235]
	v_mov_b32_e32 v134, v158
	v_mov_b32_e32 v135, v158
	v_pk_mul_f32 v[132:133], v[32:33], v[132:133]
	v_pk_mul_f32 v[130:131], v[30:31], v[130:131]
	v_pk_mul_f32 v[132:133], v[134:135], v[132:133]
	v_pk_mul_f32 v[130:131], v[158:159], v[130:131]

.LBB0_852:
	s_nop 1
	v_cvt_pk_bf16_f32 v130, v130, v131
	v_cvt_pk_bf16_f32 v131, v132, v133
	v_mov_b64_e32 v[134:135], v[24:25]
	s_and_b64 vcc, exec, s[40:41]
	v_mov_b64_e32 v[132:133], v[22:23]
	s_cbranch_vccnz .LBB0_854
	v_mov_b64_e32 v[132:133], v[236:237]
	v_mov_b64_e32 v[134:135], v[238:239]
	v_mov_b32_e32 v166, v158
	v_mov_b32_e32 v167, v158
	v_pk_mul_f32 v[134:135], v[24:25], v[134:135]
	v_pk_mul_f32 v[132:133], v[22:23], v[132:133]
	v_pk_mul_f32 v[134:135], v[166:167], v[134:135]
	v_pk_mul_f32 v[132:133], v[158:159], v[132:133]

.LBB0_858:
	v_mov_b64_e32 v[132:133], v[44:45]
	s_and_b64 vcc, exec, s[40:41]
	v_mov_b32_e32 v159, v158
	v_mov_b64_e32 v[130:131], v[42:43]
	s_cbranch_vccnz .LBB0_860
	v_mov_b64_e32 v[130:131], v[224:225]
	v_mov_b64_e32 v[132:133], v[226:227]
	v_mov_b32_e32 v134, v158
	v_mov_b32_e32 v135, v158
	v_pk_mul_f32 v[132:133], v[44:45], v[132:133]
	v_pk_mul_f32 v[130:131], v[42:43], v[130:131]
	v_pk_mul_f32 v[132:133], v[134:135], v[132:133]
	v_pk_mul_f32 v[130:131], v[158:159], v[130:131]

.LBB0_862:
	s_nop 1
	v_cvt_pk_bf16_f32 v130, v130, v131
	v_cvt_pk_bf16_f32 v131, v132, v133
	v_mov_b64_e32 v[134:135], v[36:37]
	s_and_b64 vcc, exec, s[40:41]
	v_mov_b64_e32 v[132:133], v[34:35]
	s_cbranch_vccnz .LBB0_864
	v_mov_b64_e32 v[132:133], v[228:229]
	v_mov_b64_e32 v[134:135], v[230:231]
	v_mov_b32_e32 v166, v158
	v_mov_b32_e32 v167, v158
	v_pk_mul_f32 v[134:135], v[36:37], v[134:135]
	v_pk_mul_f32 v[132:133], v[34:35], v[132:133]
	v_pk_mul_f32 v[134:135], v[166:167], v[134:135]
	v_pk_mul_f32 v[132:133], v[158:159], v[132:133]

.LBB0_866:
	v_ashrrev_i32_e32 v162, 5, v162
	v_mad_i64_i32 v[162:163], s[8:9], s0, v162, 0
	v_or_b32_e32 v162, v162, v0
	v_lshlrev_b64 v[162:163], 10, v[162:163]
	v_lshl_add_u64 v[162:163], v[156:157], 0, v[162:163]
	v_cvt_pk_bf16_f32 v132, v132, v133
	v_cvt_pk_bf16_f32 v133, v134, v135
	global_store_dwordx4 v[162:163], v[130:133], off
	s_and_b64 vcc, exec, s[40:41]
	s_nop 0
	v_mov_b64_e32 v[132:133], v[16:17]
	v_mov_b64_e32 v[130:131], v[14:15]
	s_cbranch_vccnz .LBB0_868
	v_mov_b64_e32 v[130:131], v[232:233]
	v_mov_b64_e32 v[132:133], v[234:235]
	v_mov_b32_e32 v134, v158
	v_mov_b32_e32 v135, v158
	v_pk_mul_f32 v[132:133], v[16:17], v[132:133]
	v_pk_mul_f32 v[130:131], v[14:15], v[130:131]
	v_pk_mul_f32 v[132:133], v[134:135], v[132:133]
	v_pk_mul_f32 v[130:131], v[158:159], v[130:131]

.LBB0_870:
	s_nop 1
	v_cvt_pk_bf16_f32 v130, v130, v131
	v_cvt_pk_bf16_f32 v131, v132, v133
	v_mov_b64_e32 v[134:135], v[12:13]
	s_and_b64 vcc, exec, s[40:41]
	v_mov_b64_e32 v[132:133], v[10:11]
	s_cbranch_vccnz .LBB0_872
	v_mov_b64_e32 v[132:133], v[236:237]
	v_mov_b64_e32 v[134:135], v[238:239]
	v_mov_b32_e32 v166, v158
	v_mov_b32_e32 v167, v158
	v_pk_mul_f32 v[134:135], v[12:13], v[134:135]
	v_pk_mul_f32 v[132:133], v[10:11], v[132:133]
	v_pk_mul_f32 v[134:135], v[166:167], v[134:135]
	v_pk_mul_f32 v[132:133], v[158:159], v[132:133]

.LBB0_876:
	v_mov_b64_e32 v[132:133], v[28:29]
	s_and_b64 vcc, exec, s[40:41]
	v_mov_b32_e32 v159, v158
	v_mov_b64_e32 v[130:131], v[26:27]
	s_cbranch_vccnz .LBB0_878
	v_mov_b64_e32 v[130:131], v[224:225]
	v_mov_b64_e32 v[132:133], v[226:227]
	v_mov_b32_e32 v134, v158
	v_mov_b32_e32 v135, v158
	v_pk_mul_f32 v[132:133], v[28:29], v[132:133]
	v_pk_mul_f32 v[130:131], v[26:27], v[130:131]
	v_pk_mul_f32 v[132:133], v[134:135], v[132:133]
	v_pk_mul_f32 v[130:131], v[158:159], v[130:131]

.LBB0_880:
	s_nop 1
	v_cvt_pk_bf16_f32 v130, v130, v131
	v_cvt_pk_bf16_f32 v131, v132, v133
	v_mov_b64_e32 v[134:135], v[20:21]
	s_and_b64 vcc, exec, s[40:41]
	v_mov_b64_e32 v[132:133], v[18:19]
	s_cbranch_vccnz .LBB0_882
	v_mov_b64_e32 v[132:133], v[228:229]
	v_mov_b64_e32 v[134:135], v[230:231]
	v_mov_b32_e32 v162, v158
	v_mov_b32_e32 v163, v158
	v_pk_mul_f32 v[134:135], v[20:21], v[134:135]
	v_pk_mul_f32 v[132:133], v[18:19], v[132:133]
	v_pk_mul_f32 v[134:135], v[162:163], v[134:135]
	v_pk_mul_f32 v[132:133], v[158:159], v[132:133]

.LBB0_884:
	v_ashrrev_i32_e32 v0, 5, v160
	v_mad_i64_i32 v[160:161], s[0:1], s0, v0, 0
	v_or_b32_e32 v160, v160, v151
	v_lshlrev_b64 v[160:161], 10, v[160:161]
	v_lshl_add_u64 v[156:157], v[156:157], 0, v[160:161]
	v_cvt_pk_bf16_f32 v132, v132, v133
	v_cvt_pk_bf16_f32 v133, v134, v135
	global_store_dwordx4 v[156:157], v[130:133], off
	s_and_b64 vcc, exec, s[40:41]
	s_nop 0
	v_mov_b64_e32 v[132:133], v[8:9]
	v_mov_b64_e32 v[130:131], v[6:7]
	s_cbranch_vccnz .LBB0_886
	v_mov_b64_e32 v[130:131], v[232:233]
	v_mov_b64_e32 v[132:133], v[234:235]
	v_mov_b32_e32 v134, v158
	v_mov_b32_e32 v135, v158
	v_pk_mul_f32 v[132:133], v[8:9], v[132:133]
	v_pk_mul_f32 v[130:131], v[6:7], v[130:131]
	v_pk_mul_f32 v[132:133], v[134:135], v[132:133]
	v_pk_mul_f32 v[130:131], v[158:159], v[130:131]

.LBB0_888:
	s_nop 1
	v_cvt_pk_bf16_f32 v130, v130, v131
	v_cvt_pk_bf16_f32 v131, v132, v133
	v_mov_b64_e32 v[134:135], v[4:5]
	s_and_b64 vcc, exec, s[40:41]
	v_mov_b64_e32 v[132:133], v[2:3]
	s_cbranch_vccnz .LBB0_890
	v_mov_b64_e32 v[132:133], v[236:237]
	v_mov_b64_e32 v[134:135], v[238:239]
	v_mov_b32_e32 v152, v158
	v_mov_b32_e32 v153, v158
	v_pk_mul_f32 v[134:135], v[4:5], v[134:135]
	v_pk_mul_f32 v[132:133], v[2:3], v[132:133]
	v_pk_mul_f32 v[134:135], v[152:153], v[134:135]
	v_pk_mul_f32 v[132:133], v[158:159], v[132:133]
